# prompt differential V^T image stored tile-major (16 KB contiguous per key tile) instead of 16 KB row stride; epilogue and attention main pass changed together
# baseline (speedup 1.0000x reference)
.LBB0_338:
	v_lshl_add_u32 v130, v129, 2, v174
	v_ashrrev_i32_e32 v131, 31, v130
	s_lshl_b32 s7, s78, 2
	v_lshlrev_b64 v[130:131], s6, v[130:131]
	v_mov_b32_e32 v129, v153
	s_add_u32 s54, s62, s7
	v_lshl_add_u64 v[128:129], v[130:131], 0, v[128:129]
	s_addc_u32 s55, s63, 0
	v_lshlrev_b64 v[128:129], 9, v[128:129]
	v_lshl_add_u64 v[128:129], s[54:55], 0, v[128:129]
	v_lshl_add_u64 v[128:129], v[128:129], 0, v[152:153]
	global_store_dword v[128:129], v124, off nt
	global_store_dword v[128:129], v125, off offset:512 nt
	global_store_dword v[128:129], v126, off offset:1024 nt
	global_store_dword v[128:129], v127, off offset:1536 nt
	v_lshlrev_b32_e32 v128, 7, v209
	v_mov_b32_e32 v129, v153
	v_lshl_add_u64 v[134:135], s[18:19], 0, v[128:129]
	v_cvt_pk_bf16_f32 v128, v112, v113
	v_cvt_pk_bf16_f32 v129, v114, v115
	v_cvt_pk_bf16_f32 v130, v116, v117
	v_cvt_pk_bf16_f32 v131, v118, v119
	s_nop 0
	v_permlane32_swap_b32_e32 v128, v130
	v_permlane32_swap_b32_e32 v129, v131
	s_mov_b64 s[6:7], -1
	s_and_b64 vcc, exec, s[0:1]
	v_lshl_add_u32 v132, s34, 2, v174
	s_cbranch_vccz .LBB0_340
	v_ashrrev_i32_e32 v133, 31, v132
	v_lshlrev_b64 v[136:137], 21, v[132:133]
	v_lshl_add_u64 v[136:137], v[134:135], 0, v[136:137]
	s_mov_b64 s[6:7], 0

.LBB0_342:
	v_lshrrev_b32_e32 v251, 6, v133
	v_and_b32_e32 v138, 63, v133
	v_lshl_or_b32 v138, v251, 13, v138
	v_lshlrev_b32_e32 v138, 1, v138
	v_mov_b32_e32 v139, v153
	v_lshl_add_u64 v[136:137], v[136:137], 0, v[138:139]
	global_store_dwordx4 v[136:137], v[128:131], off
	s_and_b64 vcc, exec, s[4:5]
	s_mov_b64 s[6:7], -1
	v_cvt_pk_bf16_f32 v128, v120, v121
	v_cvt_pk_bf16_f32 v129, v122, v123
	v_cvt_pk_bf16_f32 v130, v124, v125
	v_cvt_pk_bf16_f32 v131, v126, v127
	s_nop 0
	v_permlane32_swap_b32_e32 v128, v130
	v_permlane32_swap_b32_e32 v129, v131
	s_cbranch_vccnz .LBB0_344
	v_ashrrev_i32_e32 v133, 31, v132
	v_lshlrev_b64 v[136:137], 21, v[132:133]
	v_lshl_add_u64 v[136:137], v[134:135], 0, v[136:137]
	s_mov_b64 s[6:7], 0

.LBB0_346:
	v_lshrrev_b32_e32 v251, 6, v133
	v_and_b32_e32 v138, 63, v133
	v_lshl_or_b32 v138, v251, 13, v138
	v_lshlrev_b32_e32 v138, 1, v138
	v_mov_b32_e32 v139, v153
	v_lshl_add_u64 v[136:137], v[136:137], 0, v[138:139]
	s_and_b64 vcc, exec, s[4:5]
	s_mov_b64 s[6:7], -1
	global_store_dwordx4 v[136:137], v[128:131], off
	s_cbranch_vccnz .LBB0_348
	s_nop 0
	v_or_b32_e32 v128, s52, v172
	s_mov_b64 s[6:7], 0

.LBB0_366:
	v_lshl_add_u32 v130, v129, 2, v174
	v_ashrrev_i32_e32 v131, 31, v130
	s_lshl_b32 s7, s78, 2
	v_lshlrev_b64 v[130:131], s6, v[130:131]
	v_mov_b32_e32 v129, v153
	s_add_u32 s54, s62, s7
	v_lshl_add_u64 v[128:129], v[130:131], 0, v[128:129]
	s_addc_u32 s55, s63, 0
	v_lshlrev_b64 v[128:129], 9, v[128:129]
	v_lshl_add_u64 v[128:129], s[54:55], 0, v[128:129]
	v_or_b32_e32 v176, 32, v209
	v_lshl_add_u64 v[128:129], v[128:129], 0, v[152:153]
	global_store_dword v[128:129], v108, off offset:128 nt
	global_store_dword v[128:129], v109, off offset:640 nt
	global_store_dword v[128:129], v110, off offset:1152 nt
	global_store_dword v[128:129], v111, off offset:1664 nt
	v_lshlrev_b32_e32 v128, 7, v176
	v_mov_b32_e32 v129, v153
	v_lshl_add_u64 v[136:137], s[18:19], 0, v[128:129]
	v_cvt_pk_bf16_f32 v128, v96, v97
	v_cvt_pk_bf16_f32 v129, v98, v99
	v_cvt_pk_bf16_f32 v130, v100, v101
	v_cvt_pk_bf16_f32 v131, v102, v103
	s_nop 0
	v_permlane32_swap_b32_e32 v128, v130
	v_permlane32_swap_b32_e32 v129, v131
	s_and_b64 vcc, exec, s[4:5]
	s_mov_b64 s[6:7], -1
	s_cbranch_vccnz .LBB0_368
	v_ashrrev_i32_e32 v133, 31, v132
	v_lshlrev_b64 v[138:139], 21, v[132:133]
	v_lshl_add_u64 v[138:139], v[136:137], 0, v[138:139]
	s_mov_b64 s[6:7], 0

.LBB0_370:
	v_lshrrev_b32_e32 v251, 6, v133
	v_and_b32_e32 v220, 63, v133
	v_lshl_or_b32 v220, v251, 13, v220
	v_lshlrev_b32_e32 v220, 1, v220
	v_mov_b32_e32 v221, v153
	v_lshl_add_u64 v[138:139], v[138:139], 0, v[220:221]
	global_store_dwordx4 v[138:139], v[128:131], off
	s_and_b64 vcc, exec, s[4:5]
	s_mov_b64 s[6:7], -1
	v_cvt_pk_bf16_f32 v128, v104, v105
	v_cvt_pk_bf16_f32 v129, v106, v107
	v_cvt_pk_bf16_f32 v130, v108, v109
	v_cvt_pk_bf16_f32 v131, v110, v111
	s_nop 0
	v_permlane32_swap_b32_e32 v128, v130
	v_permlane32_swap_b32_e32 v129, v131
	s_cbranch_vccnz .LBB0_372
	v_ashrrev_i32_e32 v133, 31, v132
	v_lshlrev_b64 v[138:139], 21, v[132:133]
	v_lshl_add_u64 v[138:139], v[136:137], 0, v[138:139]
	s_mov_b64 s[6:7], 0

.LBB0_374:
	v_lshrrev_b32_e32 v251, 6, v133
	v_and_b32_e32 v220, 63, v133
	v_lshl_or_b32 v220, v251, 13, v220
	v_lshlrev_b32_e32 v220, 1, v220
	v_mov_b32_e32 v221, v153
	v_lshl_add_u64 v[138:139], v[138:139], 0, v[220:221]
	s_and_b64 vcc, exec, s[4:5]
	s_mov_b64 s[6:7], -1
	global_store_dwordx4 v[138:139], v[128:131], off
	s_cbranch_vccnz .LBB0_376
	s_nop 0
	v_or_b32_e32 v128, s52, v172
	s_mov_b64 s[6:7], 0

.LBB0_394:
	v_lshl_add_u32 v130, v129, 2, v174
	v_ashrrev_i32_e32 v131, 31, v130
	s_lshl_b32 s7, s78, 2
	v_lshlrev_b64 v[130:131], s6, v[130:131]
	v_mov_b32_e32 v129, v153
	s_add_u32 s54, s62, s7
	v_lshl_add_u64 v[128:129], v[130:131], 0, v[128:129]
	s_addc_u32 s55, s63, 0
	v_lshlrev_b64 v[128:129], 9, v[128:129]
	v_lshl_add_u64 v[128:129], s[54:55], 0, v[128:129]
	v_or_b32_e32 v177, 64, v209
	v_lshl_add_u64 v[128:129], v[128:129], 0, v[152:153]
	global_store_dword v[128:129], v92, off offset:256 nt
	global_store_dword v[128:129], v93, off offset:768 nt
	global_store_dword v[128:129], v94, off offset:1280 nt
	global_store_dword v[128:129], v95, off offset:1792 nt
	v_lshlrev_b32_e32 v128, 7, v177
	v_mov_b32_e32 v129, v153
	v_lshl_add_u64 v[138:139], s[18:19], 0, v[128:129]
	v_cvt_pk_bf16_f32 v128, v80, v81
	v_cvt_pk_bf16_f32 v129, v82, v83
	v_cvt_pk_bf16_f32 v130, v84, v85
	v_cvt_pk_bf16_f32 v131, v86, v87
	s_nop 0
	v_permlane32_swap_b32_e32 v128, v130
	v_permlane32_swap_b32_e32 v129, v131
	s_and_b64 vcc, exec, s[4:5]
	s_mov_b64 s[6:7], -1
	s_cbranch_vccnz .LBB0_396
	v_ashrrev_i32_e32 v133, 31, v132
	v_lshlrev_b64 v[148:149], 21, v[132:133]
	v_lshl_add_u64 v[148:149], v[138:139], 0, v[148:149]
	s_mov_b64 s[6:7], 0

.LBB0_398:
	v_lshrrev_b32_e32 v251, 6, v133
	v_and_b32_e32 v220, 63, v133
	v_lshl_or_b32 v220, v251, 13, v220
	v_lshlrev_b32_e32 v220, 1, v220
	v_mov_b32_e32 v221, v153
	v_lshl_add_u64 v[148:149], v[148:149], 0, v[220:221]
	global_store_dwordx4 v[148:149], v[128:131], off
	s_and_b64 vcc, exec, s[4:5]
	s_mov_b64 s[6:7], -1
	v_cvt_pk_bf16_f32 v128, v88, v89
	v_cvt_pk_bf16_f32 v129, v90, v91
	v_cvt_pk_bf16_f32 v130, v92, v93
	v_cvt_pk_bf16_f32 v131, v94, v95
	s_nop 0
	v_permlane32_swap_b32_e32 v128, v130
	v_permlane32_swap_b32_e32 v129, v131
	s_cbranch_vccnz .LBB0_400
	v_ashrrev_i32_e32 v133, 31, v132
	v_lshlrev_b64 v[148:149], 21, v[132:133]
	v_lshl_add_u64 v[148:149], v[138:139], 0, v[148:149]
	s_mov_b64 s[6:7], 0

.LBB0_402:
	v_lshrrev_b32_e32 v251, 6, v133
	v_and_b32_e32 v220, 63, v133
	v_lshl_or_b32 v220, v251, 13, v220
	v_lshlrev_b32_e32 v220, 1, v220
	v_mov_b32_e32 v221, v153
	v_lshl_add_u64 v[148:149], v[148:149], 0, v[220:221]
	s_and_b64 vcc, exec, s[4:5]
	s_mov_b64 s[6:7], -1
	global_store_dwordx4 v[148:149], v[128:131], off
	s_cbranch_vccnz .LBB0_404
	s_mov_b64 s[6:7], 0

.LBB0_422:
	v_lshl_add_u32 v128, v128, 2, v174
	v_ashrrev_i32_e32 v129, 31, v128
	s_lshl_b32 s7, s78, 2
	v_lshlrev_b64 v[128:129], s6, v[128:129]
	v_mov_b32_e32 v147, v153
	s_add_u32 s54, s62, s7
	v_lshl_add_u64 v[128:129], v[128:129], 0, v[146:147]
	s_addc_u32 s55, s63, 0
	v_lshlrev_b64 v[128:129], 9, v[128:129]
	v_lshl_add_u64 v[128:129], s[54:55], 0, v[128:129]
	v_or_b32_e32 v212, 0x60, v209
	v_lshl_add_u64 v[128:129], v[128:129], 0, v[152:153]
	global_store_dword v[128:129], v76, off offset:384 nt
	global_store_dword v[128:129], v77, off offset:896 nt
	global_store_dword v[128:129], v78, off offset:1408 nt
	global_store_dword v[128:129], v79, off offset:1920 nt
	v_lshlrev_b32_e32 v128, 7, v212
	v_mov_b32_e32 v129, v153
	v_lshl_add_u64 v[140:141], s[18:19], 0, v[128:129]
	v_cvt_pk_bf16_f32 v128, v64, v65
	v_cvt_pk_bf16_f32 v129, v66, v67
	v_cvt_pk_bf16_f32 v130, v68, v69
	v_cvt_pk_bf16_f32 v131, v70, v71
	s_nop 0
	v_permlane32_swap_b32_e32 v128, v130
	v_permlane32_swap_b32_e32 v129, v131
	s_and_b64 vcc, exec, s[4:5]
	s_mov_b64 s[6:7], -1
	s_cbranch_vccnz .LBB0_424
	v_ashrrev_i32_e32 v133, 31, v132
	v_lshlrev_b64 v[142:143], 21, v[132:133]
	v_lshl_add_u64 v[142:143], v[140:141], 0, v[142:143]
	s_mov_b64 s[6:7], 0

.LBB0_426:
	v_lshrrev_b32_e32 v251, 6, v150
	v_and_b32_e32 v144, 63, v150
	v_lshl_or_b32 v144, v251, 13, v144
	v_lshlrev_b32_e32 v144, 1, v144
	v_mov_b32_e32 v145, v153
	v_lshl_add_u64 v[142:143], v[142:143], 0, v[144:145]
	global_store_dwordx4 v[142:143], v[128:131], off
	s_and_b64 vcc, exec, s[4:5]
	s_mov_b64 s[6:7], -1
	v_cvt_pk_bf16_f32 v128, v72, v73
	v_cvt_pk_bf16_f32 v129, v74, v75
	v_cvt_pk_bf16_f32 v130, v76, v77
	v_cvt_pk_bf16_f32 v131, v78, v79
	s_nop 0
	v_permlane32_swap_b32_e32 v128, v130
	v_permlane32_swap_b32_e32 v129, v131
	s_cbranch_vccnz .LBB0_428
	v_ashrrev_i32_e32 v133, 31, v132
	v_lshlrev_b64 v[142:143], 21, v[132:133]
	v_lshl_add_u64 v[142:143], v[140:141], 0, v[142:143]
	s_mov_b64 s[6:7], 0

.LBB0_430:
	v_lshrrev_b32_e32 v251, 6, v215
	v_and_b32_e32 v144, 63, v215
	v_lshl_or_b32 v144, v251, 13, v144
	v_lshlrev_b32_e32 v144, 1, v144
	v_mov_b32_e32 v145, v153
	v_or_b32_e32 v221, 32, v171
	v_lshl_add_u64 v[142:143], v[142:143], 0, v[144:145]
	v_or_b32_e32 v227, v221, v170
	global_store_dwordx4 v[142:143], v[128:131], off
	s_mov_b64 s[6:7], -1
	s_and_b64 vcc, exec, s[4:5]
	v_or_b32_e32 v142, s52, v227
	s_cbranch_vccnz .LBB0_432
	v_or_b32_e32 v128, s52, v227
	s_mov_b64 s[6:7], 0

.LBB0_454:
	v_lshrrev_b32_e32 v251, 6, v133
	v_and_b32_e32 v230, 63, v133
	v_lshl_or_b32 v230, v251, 13, v230
	v_lshlrev_b32_e32 v230, 1, v230
	v_mov_b32_e32 v231, v153
	v_lshl_add_u64 v[150:151], v[150:151], 0, v[230:231]
	global_store_dwordx4 v[150:151], v[128:131], off
	s_and_b64 vcc, exec, s[4:5]
	s_mov_b64 s[6:7], -1
	v_cvt_pk_bf16_f32 v128, v56, v57
	v_cvt_pk_bf16_f32 v129, v58, v59
	v_cvt_pk_bf16_f32 v130, v60, v61
	v_cvt_pk_bf16_f32 v131, v62, v63
	s_nop 0
	v_permlane32_swap_b32_e32 v128, v130
	v_permlane32_swap_b32_e32 v129, v131
	s_cbranch_vccnz .LBB0_456
	v_ashrrev_i32_e32 v133, 31, v132
	v_lshlrev_b64 v[150:151], 21, v[132:133]
	v_lshl_add_u64 v[150:151], v[134:135], 0, v[150:151]
	s_mov_b64 s[6:7], 0

.LBB0_458:
	v_lshrrev_b32_e32 v251, 6, v133
	v_and_b32_e32 v134, 63, v133
	v_lshl_or_b32 v134, v251, 13, v134
	v_lshlrev_b32_e32 v134, 1, v134
	v_mov_b32_e32 v135, v153
	v_lshl_add_u64 v[134:135], v[150:151], 0, v[134:135]
	s_and_b64 vcc, exec, s[4:5]
	s_mov_b64 s[6:7], -1
	global_store_dwordx4 v[134:135], v[128:131], off
	s_cbranch_vccnz .LBB0_460
	s_nop 0
	v_or_b32_e32 v128, s52, v227
	s_mov_b64 s[6:7], 0

.LBB0_482:
	v_lshrrev_b32_e32 v251, 6, v133
	v_and_b32_e32 v150, 63, v133
	v_lshl_or_b32 v150, v251, 13, v150
	v_lshlrev_b32_e32 v150, 1, v150
	v_mov_b32_e32 v151, v153
	v_lshl_add_u64 v[134:135], v[134:135], 0, v[150:151]
	global_store_dwordx4 v[134:135], v[128:131], off
	s_and_b64 vcc, exec, s[4:5]
	s_mov_b64 s[6:7], -1
	v_cvt_pk_bf16_f32 v128, v40, v41
	v_cvt_pk_bf16_f32 v129, v42, v43
	v_cvt_pk_bf16_f32 v130, v44, v45
	v_cvt_pk_bf16_f32 v131, v46, v47
	s_nop 0
	v_permlane32_swap_b32_e32 v128, v130
	v_permlane32_swap_b32_e32 v129, v131
	s_cbranch_vccnz .LBB0_484
	v_ashrrev_i32_e32 v133, 31, v132
	v_lshlrev_b64 v[134:135], 21, v[132:133]
	v_lshl_add_u64 v[134:135], v[136:137], 0, v[134:135]
	s_mov_b64 s[6:7], 0

.LBB0_486:
	v_lshrrev_b32_e32 v251, 6, v133
	v_and_b32_e32 v136, 63, v133
	v_lshl_or_b32 v136, v251, 13, v136
	v_lshlrev_b32_e32 v136, 1, v136
	v_mov_b32_e32 v137, v153
	v_lshl_add_u64 v[134:135], v[134:135], 0, v[136:137]
	s_and_b64 vcc, exec, s[4:5]
	s_mov_b64 s[6:7], -1
	global_store_dwordx4 v[134:135], v[128:131], off
	s_cbranch_vccnz .LBB0_488
	s_nop 0
	v_or_b32_e32 v128, s52, v227
	s_mov_b64 s[6:7], 0

.LBB0_510:
	v_lshrrev_b32_e32 v251, 6, v133
	v_and_b32_e32 v136, 63, v133
	v_lshl_or_b32 v136, v251, 13, v136
	v_lshlrev_b32_e32 v136, 1, v136
	v_mov_b32_e32 v137, v153
	v_lshl_add_u64 v[134:135], v[134:135], 0, v[136:137]
	global_store_dwordx4 v[134:135], v[128:131], off
	s_and_b64 vcc, exec, s[4:5]
	s_mov_b64 s[6:7], -1
	v_cvt_pk_bf16_f32 v128, v24, v25
	v_cvt_pk_bf16_f32 v129, v26, v27
	v_cvt_pk_bf16_f32 v130, v28, v29
	v_cvt_pk_bf16_f32 v131, v30, v31
	s_nop 0
	v_permlane32_swap_b32_e32 v128, v130
	v_permlane32_swap_b32_e32 v129, v131
	s_cbranch_vccnz .LBB0_512
	v_ashrrev_i32_e32 v133, 31, v132
	v_lshlrev_b64 v[134:135], 21, v[132:133]
	v_lshl_add_u64 v[134:135], v[138:139], 0, v[134:135]
	s_mov_b64 s[6:7], 0

.LBB0_514:
	v_lshrrev_b32_e32 v251, 6, v133
	v_and_b32_e32 v136, 63, v133
	v_lshl_or_b32 v136, v251, 13, v136
	v_lshlrev_b32_e32 v136, 1, v136
	v_mov_b32_e32 v137, v153
	v_lshl_add_u64 v[134:135], v[134:135], 0, v[136:137]
	s_and_b64 vcc, exec, s[4:5]
	s_mov_b64 s[6:7], -1
	global_store_dwordx4 v[134:135], v[128:131], off
	s_cbranch_vccnz .LBB0_516
	s_mov_b64 s[6:7], 0

.LBB0_538:
	v_lshrrev_b32_e32 v251, 6, v213
	v_and_b32_e32 v152, 63, v213
	v_lshl_or_b32 v152, v251, 13, v152
	v_lshlrev_b32_e32 v152, 1, v152
	v_lshl_add_u64 v[134:135], v[134:135], 0, v[152:153]
	global_store_dwordx4 v[134:135], v[128:131], off
	s_and_b64 vcc, exec, s[4:5]
	s_mov_b64 s[6:7], -1
	v_cvt_pk_bf16_f32 v128, v8, v9
	v_cvt_pk_bf16_f32 v129, v10, v11
	v_cvt_pk_bf16_f32 v130, v12, v13
	v_cvt_pk_bf16_f32 v131, v14, v15
	s_nop 0
	v_permlane32_swap_b32_e32 v128, v130
	v_permlane32_swap_b32_e32 v129, v131
	s_cbranch_vccnz .LBB0_540
	v_ashrrev_i32_e32 v133, 31, v132
	v_lshlrev_b64 v[132:133], 21, v[132:133]
	v_lshl_add_u64 v[134:135], v[140:141], 0, v[132:133]
	s_mov_b64 s[6:7], 0

.LBB0_542:
	v_lshrrev_b32_e32 v251, 6, v214
	v_and_b32_e32 v152, 63, v214
	v_lshl_or_b32 v152, v251, 13, v152
	v_lshlrev_b32_e32 v152, 1, v152
	v_lshl_add_u64 v[132:133], v[134:135], 0, v[152:153]
	s_mov_b64 s[6:7], 0
	global_store_dwordx4 v[132:133], v[128:131], off

.LBB0_849:
	s_andn2_b64 vcc, exec, s[44:45]
	s_cbranch_vccnz .LBB0_851
	s_lshl_b32 s47, s50, 6
	s_lshl_b64 s[30:31], s[0:1], 21
	s_lshl_b32 s1, s50, 14
	s_add_u32 s4, s58, s30
	s_addc_u32 s5, s59, s31
	s_add_u32 s4, s4, s1
	s_addc_u32 s5, s5, 0
	s_add_u32 s40, s60, s30
	s_addc_u32 s41, s61, s31
	s_add_u32 s42, s64, s30
	s_addc_u32 s43, s65, s31
	s_mov_b32 s48, 64
	s_add_i32 s51, s47, 64
	s_mov_b64 s[44:45], 64
	s_mov_b32 s49, 13
	s_mov_b32 s52, s47
	s_branch .LBB0_852

.LBB0_852:
	s_movk_i32 s98, 0x180
	s_and_b64 s[100:101], s[36:37], exec
	s_cselect_b32 s98, s98, 0x200
	s_add_u32 s100, s66, s98
	s_addc_u32 s101, s67, 0
	s_lshl_b32 s98, s0, 3
	s_ashr_i32 s99, s98, 31
	s_add_u32 s100, s100, s98
	s_addc_u32 s101, s101, s99
	global_load_dwordx2 v[252:253], v1, s[100:101]
	s_cmp_eq_u32 s48, 64
	s_cselect_b32 s98, 8, 1
	s_cselect_b32 s100, s24, s26
	s_mov_b32 s101, -1
	v_ashrrev_i32_e32 v218, 7, v6
	v_and_b32_e32 v176, 31, v6
	v_lshlrev_b32_e32 v165, 5, v218
	v_or_b32_e32 v164, v165, v176
	s_add_i32 s1, s48, -1
	v_min_i32_e32 v66, s1, v164
	v_ashrrev_i32_e32 v0, 6, v6
	v_ashrrev_i32_e32 v67, 31, v66
	v_and_b32_e32 v217, 1, v0
	v_lshlrev_b64 v[2:3], 8, v[66:67]
	s_waitcnt vmcnt(5)
	v_bfe_u32 v138, v6, 5, 1
	v_lshl_add_u64 v[2:3], s[4:5], 0, v[2:3]
	v_lshlrev_b32_e32 v68, 7, v217
	v_mov_b32_e32 v69, v1
	v_lshl_add_u64 v[2:3], v[2:3], 0, v[68:69]
	v_lshlrev_b32_e32 v70, 4, v138
	v_mov_b32_e32 v71, v1
	v_lshl_add_u64 v[2:3], v[2:3], 0, v[70:71]
	global_load_dwordx4 v[112:115], v[2:3], off
	global_load_dwordx4 v[116:119], v[2:3], off offset:32
	global_load_dwordx4 v[120:123], v[2:3], off offset:64
	global_load_dwordx4 v[124:127], v[2:3], off offset:96
	v_and_b32_e32 v171, 63, v6
	v_cmp_eq_u32_e32 vcc, 0, v171
	s_waitcnt vmcnt(3)
	v_and_b32_e32 v3, 0xffff0000, v112
	v_lshlrev_b32_e32 v2, 16, v112
	v_mul_f32_e32 v3, v3, v3
	v_fmac_f32_e32 v3, v2, v2
	v_lshlrev_b32_e32 v2, 16, v113
	v_fmac_f32_e32 v3, v2, v2
	v_and_b32_e32 v2, 0xffff0000, v113
	v_fmac_f32_e32 v3, v2, v2
	v_lshlrev_b32_e32 v2, 16, v114
	v_fmac_f32_e32 v3, v2, v2
	v_and_b32_e32 v2, 0xffff0000, v114
	v_fmac_f32_e32 v3, v2, v2
	v_lshlrev_b32_e32 v2, 16, v115
	v_fmac_f32_e32 v3, v2, v2
	v_and_b32_e32 v2, 0xffff0000, v115
	s_waitcnt vmcnt(2)
	v_and_b32_e32 v4, 0xffff0000, v116
	v_fmac_f32_e32 v3, v2, v2
	v_lshlrev_b32_e32 v2, 16, v116
	v_mul_f32_e32 v4, v4, v4
	v_fmac_f32_e32 v4, v2, v2
	v_lshlrev_b32_e32 v2, 16, v117
	v_fmac_f32_e32 v4, v2, v2
	v_and_b32_e32 v2, 0xffff0000, v117
	v_fmac_f32_e32 v4, v2, v2
	v_lshlrev_b32_e32 v2, 16, v118
	v_fmac_f32_e32 v4, v2, v2
	v_and_b32_e32 v2, 0xffff0000, v118
	v_fmac_f32_e32 v4, v2, v2
	v_lshlrev_b32_e32 v2, 16, v119
	v_fmac_f32_e32 v4, v2, v2
	v_and_b32_e32 v2, 0xffff0000, v119
	v_fmac_f32_e32 v4, v2, v2
	v_add_f32_e32 v2, v3, v4
	s_waitcnt vmcnt(1)
	v_and_b32_e32 v4, 0xffff0000, v120
	v_lshlrev_b32_e32 v3, 16, v120
	v_mul_f32_e32 v4, v4, v4
	v_fmac_f32_e32 v4, v3, v3
	v_lshlrev_b32_e32 v3, 16, v121
	v_fmac_f32_e32 v4, v3, v3
	v_and_b32_e32 v3, 0xffff0000, v121
	v_fmac_f32_e32 v4, v3, v3
	v_lshlrev_b32_e32 v3, 16, v122
	v_fmac_f32_e32 v4, v3, v3
	v_and_b32_e32 v3, 0xffff0000, v122
	v_fmac_f32_e32 v4, v3, v3
	v_lshlrev_b32_e32 v3, 16, v123
	v_fmac_f32_e32 v4, v3, v3
	v_and_b32_e32 v3, 0xffff0000, v123
	v_fmac_f32_e32 v4, v3, v3
	v_add_f32_e32 v2, v2, v4
	s_waitcnt vmcnt(0)
	v_and_b32_e32 v4, 0xffff0000, v124
	v_lshlrev_b32_e32 v3, 16, v124
	v_mul_f32_e32 v4, v4, v4
	v_fmac_f32_e32 v4, v3, v3
	v_lshlrev_b32_e32 v3, 16, v125
	v_fmac_f32_e32 v4, v3, v3
	v_and_b32_e32 v3, 0xffff0000, v125
	v_fmac_f32_e32 v4, v3, v3
	v_lshlrev_b32_e32 v3, 16, v126
	v_fmac_f32_e32 v4, v3, v3
	v_and_b32_e32 v3, 0xffff0000, v126
	v_fmac_f32_e32 v4, v3, v3
	v_lshlrev_b32_e32 v3, 16, v127
	v_fmac_f32_e32 v4, v3, v3
	v_and_b32_e32 v3, 0xffff0000, v127
	v_fmac_f32_e32 v4, v3, v3
	v_add_f32_e32 v2, v2, v4
	ds_bpermute_b32 v3, v205, v2
	s_waitcnt lgkmcnt(0)
	v_add_f32_e32 v2, v2, v3
	ds_bpermute_b32 v3, v207, v2
	s_waitcnt lgkmcnt(0)
	v_max_f32_e32 v3, v3, v3
	v_max_f32_e32 v2, v2, v3
	ds_bpermute_b32 v3, v208, v2
	s_waitcnt lgkmcnt(0)
	v_max_f32_e32 v3, v3, v3
	v_max_f32_e32 v2, v2, v3
	ds_bpermute_b32 v3, v209, v2
	s_waitcnt lgkmcnt(0)
	v_max_f32_e32 v3, v3, v3
	v_max_f32_e32 v2, v2, v3
	ds_bpermute_b32 v3, v210, v2
	s_waitcnt lgkmcnt(0)
	v_max_f32_e32 v3, v3, v3
	v_max_f32_e32 v2, v2, v3
	ds_bpermute_b32 v3, v206, v2
	s_and_saveexec_b64 s[4:5], vcc
	s_cbranch_execz .LBB0_854
	s_waitcnt lgkmcnt(0)
	v_max_f32_e32 v3, v3, v3
	v_max_f32_e32 v2, v2, v2
	v_lshl_add_u32 v0, v0, 2, v203
	v_max_f32_e32 v2, v2, v3
	ds_write_b32 v0, v2

.LBB0_867:
	v_lshlrev_b64 v[172:173], 1, v[94:95]
	v_lshl_add_u64 v[2:3], v[102:103], 0, v[172:173]
	global_load_dwordx4 v[128:131], v[2:3], off
	v_lshlrev_b64 v[2:3], 1, v[78:79]
	v_lshl_add_u64 v[6:7], s[42:43], 0, v[2:3]
	s_lshl_b64 s[0:1], s[6:7], s98
	v_lshl_add_u64 v[6:7], v[6:7], 0, s[0:1]
	v_lshlrev_b64 v[174:175], 1, v[72:73]
	v_lshl_add_u64 v[6:7], v[6:7], 0, v[174:175]
	global_load_dwordx4 v[132:135], v[6:7], off
	v_lshl_add_u64 v[6:7], s[40:41], 0, v[80:81]
	v_lshl_add_u64 v[6:7], v[6:7], 0, v[172:173]
	v_lshlrev_b32_e32 v234, 3, v138
	global_load_dwordx4 v[136:139], v[6:7], off
	v_lshlrev_b64 v[6:7], 1, v[82:83]
	v_lshl_add_u64 v[8:9], s[42:43], 0, v[6:7]
	v_lshl_add_u64 v[8:9], v[8:9], 0, s[0:1]
	v_lshl_add_u64 v[8:9], v[8:9], 0, v[174:175]
	global_load_dwordx4 v[140:143], v[8:9], off
	v_lshl_add_u64 v[8:9], s[40:41], 0, v[84:85]
	v_lshl_add_u64 v[8:9], v[8:9], 0, v[172:173]
	global_load_dwordx4 v[144:147], v[8:9], off
	v_lshlrev_b64 v[8:9], 1, v[86:87]
	v_lshl_add_u64 v[10:11], s[42:43], 0, v[8:9]
	v_lshl_add_u64 v[10:11], v[10:11], 0, s[0:1]
	v_lshl_add_u64 v[10:11], v[10:11], 0, v[174:175]
	global_load_dwordx4 v[148:151], v[10:11], off
	v_lshl_add_u64 v[10:11], s[40:41], 0, v[88:89]
	v_lshl_add_u64 v[10:11], v[10:11], 0, v[172:173]
	global_load_dwordx4 v[152:155], v[10:11], off
	v_lshlrev_b64 v[10:11], 1, v[90:91]
	v_lshl_add_u64 v[14:15], s[42:43], 0, v[10:11]
	v_lshl_add_u64 v[14:15], v[14:15], 0, s[0:1]
	v_lshl_add_u64 v[14:15], v[14:15], 0, v[174:175]
	global_load_dwordx4 v[156:159], v[14:15], off
	s_sub_i32 s30, s6, 64
	s_ashr_i32 s31, s30, 31
	s_lshl_b64 s[30:31], s[30:31], s98
	s_add_u32 s30, s30, s42
	s_addc_u32 s31, s31, s43
	v_fmaak_f32 v0, -2.0, v67, 0xc3160000
	v_mov_b64_e32 v[4:5], s[30:31]
	v_mov_b32_e32 v14, v1
	v_mov_b32_e32 v15, v1
	v_cndmask_b32_e64 v235, v212, v0, s[4:5]
	v_lshl_add_u64 v[178:179], v[4:5], 0, v[10:11]
	v_lshl_add_u64 v[180:181], v[4:5], 0, v[8:9]
	v_lshl_add_u64 v[182:183], v[4:5], 0, v[6:7]
	v_lshl_add_u64 v[184:185], v[4:5], 0, v[2:3]
	v_subrev_u32_e32 v238, 64, v75
	v_sub_u32_e32 v237, v66, v170
	v_subrev_u32_e32 v240, s34, v13
	v_mov_b32_e32 v0, v1
	v_mov_b32_e32 v2, v1
	v_mov_b32_e32 v3, v1
	v_mov_b32_e32 v4, v1
	v_mov_b32_e32 v5, v1
	v_mov_b32_e32 v6, v1
	v_mov_b32_e32 v7, v1
	v_mov_b32_e32 v8, v1
	v_mov_b32_e32 v9, v1
	v_mov_b32_e32 v10, v1
	v_mov_b32_e32 v11, v1
	v_mov_b32_e32 v12, v1
	v_mov_b32_e32 v13, v1
	v_mov_b64_e32 v[30:31], v[14:15]
	s_waitcnt vmcnt(12)
	v_mov_b64_e32 v[46:47], v[14:15]
	s_waitcnt vmcnt(8)
	v_mov_b64_e32 v[62:63], v[14:15]
	v_mov_b64_e32 v[78:79], v[14:15]
	v_mul_u32_u24_e32 v236, 0x88, v176
	v_lshl_add_u64 v[176:177], s[40:41], 0, v[92:93]
	v_lshl_add_u64 v[186:187], s[40:41], 0, v[96:97]
	v_lshl_add_u64 v[188:189], s[40:41], 0, v[98:99]
	v_lshl_add_u64 v[190:191], s[40:41], 0, v[100:101]
	s_mov_b32 s6, 0
	v_mov_b32_e32 v239, 0
	v_mov_b32_e32 v241, v170
	v_mov_b64_e32 v[28:29], v[12:13]
	v_mov_b64_e32 v[26:27], v[10:11]
	v_mov_b64_e32 v[24:25], v[8:9]
	v_mov_b64_e32 v[22:23], v[6:7]
	v_mov_b64_e32 v[20:21], v[4:5]
	v_mov_b64_e32 v[18:19], v[2:3]
	v_mov_b64_e32 v[16:17], v[0:1]
	v_mov_b64_e32 v[44:45], v[12:13]
	v_mov_b64_e32 v[42:43], v[10:11]
	v_mov_b64_e32 v[40:41], v[8:9]
	v_mov_b64_e32 v[38:39], v[6:7]
	v_mov_b64_e32 v[36:37], v[4:5]
	v_mov_b64_e32 v[34:35], v[2:3]
	v_mov_b64_e32 v[32:33], v[0:1]
	v_mov_b64_e32 v[60:61], v[12:13]
	v_mov_b64_e32 v[58:59], v[10:11]
	v_mov_b64_e32 v[56:57], v[8:9]
	v_mov_b64_e32 v[54:55], v[6:7]
	v_mov_b64_e32 v[52:53], v[4:5]
	v_mov_b64_e32 v[50:51], v[2:3]
	v_mov_b64_e32 v[48:49], v[0:1]
	v_mov_b64_e32 v[76:77], v[12:13]
	v_mov_b64_e32 v[74:75], v[10:11]
	v_mov_b64_e32 v[72:73], v[8:9]
	v_mov_b64_e32 v[70:71], v[6:7]
	v_mov_b64_e32 v[68:69], v[4:5]
	v_mov_b64_e32 v[66:67], v[2:3]
	v_mov_b64_e32 v[64:65], v[0:1]
	s_mov_b32 s42, 0
	s_branch .LBB0_869

.LBB0_871:
	s_add_i32 s0, s0, -1
	s_cmp_ge_i32 s0, s52
	s_cselect_b64 s[0:1], -1, 0
	s_mov_b64 s[4:5], -1
	s_and_b64 vcc, exec, s[0:1]
	s_mov_b64 s[40:41], -1
	s_waitcnt lgkmcnt(0)
	s_barrier
	s_cbranch_vccnz .Ldiff_diag
	v_subrev_u32_e32 v0, 63, v240
	v_cvt_f32_i32_e32 v0, v0
	v_mul_f32_e64 v0, -v166, v0
	v_cmp_nlt_f32_e32 vcc, v0, v235
	s_cbranch_vccz .LBB0_878
	v_add_u32_e32 v243, s43, v228
	v_add3_u32 v243, v243, v229, v230
	ds_read_b128 v[2:5], v243
	ds_read_b128 v[6:9], v243 offset:32
	ds_read_b128 v[10:13], v243 offset:64
	ds_read_b128 v[252:255], v243 offset:96
	v_add3_u32 v251, s43, v236, v234
	v_add_u32_e32 v242, s34, v238
	v_cvt_f32_i32_e32 v242, v242
	v_add_u32_e32 v251, 0x4400, v251
	v_fma_f32 v242, v166, v242, -v233
	v_mov_b32_e32 v96, v242
	v_add_f32_e32 v97, v166, v242
	v_fmamk_f32 v98, v166, 0x40000000, v242
	v_fmamk_f32 v99, v166, 0x40400000, v242
	v_fmamk_f32 v100, v166, 0x41000000, v242
	v_fmamk_f32 v101, v166, 0x41100000, v242
	v_fmamk_f32 v102, v166, 0x41200000, v242
	v_fmamk_f32 v103, v166, 0x41300000, v242
	v_fmamk_f32 v104, v166, 0x41800000, v242
	v_fmamk_f32 v105, v166, 0x41880000, v242
	v_fmamk_f32 v106, v166, 0x41900000, v242
	v_fmamk_f32 v107, v166, 0x41980000, v242
	v_fmamk_f32 v108, v166, 0x41c00000, v242
	v_fmamk_f32 v109, v166, 0x41c80000, v242
	v_fmamk_f32 v110, v166, 0x41d00000, v242
	v_fmamk_f32 v111, v166, 0x41d80000, v242
	v_fmamk_f32 v80, v166, 0x42000000, v242
	v_fmamk_f32 v81, v166, 0x42040000, v242
	v_fmamk_f32 v82, v166, 0x42080000, v242
	v_fmamk_f32 v83, v166, 0x420c0000, v242
	v_fmamk_f32 v84, v166, 0x42200000, v242
	v_fmamk_f32 v85, v166, 0x42240000, v242
	v_fmamk_f32 v86, v166, 0x42280000, v242
	v_fmamk_f32 v87, v166, 0x422c0000, v242
	v_fmamk_f32 v88, v166, 0x42400000, v242
	v_fmamk_f32 v89, v166, 0x42440000, v242
	v_fmamk_f32 v90, v166, 0x42480000, v242
	v_fmamk_f32 v91, v166, 0x424c0000, v242
	v_fmamk_f32 v92, v166, 0x42600000, v242
	v_fmamk_f32 v93, v166, 0x42640000, v242
	v_fmamk_f32 v94, v166, 0x42680000, v242
	v_fmamk_f32 v95, v166, 0x426c0000, v242
	s_waitcnt lgkmcnt(3)
	v_mfma_f32_32x32x16_bf16 v[96:111], v[2:5], v[112:115], v[96:111]
	ds_read_b128 v[2:5], v243 offset:8704
	v_lshl_add_u64 v[176:177], v[176:177], 0, s[24:25]
	v_lshl_add_u64 v[178:179], v[178:179], 0, s[100:101]
	s_waitcnt lgkmcnt(3)
	v_mfma_f32_32x32x16_bf16 v[96:111], v[6:9], v[116:119], v[96:111]
	ds_read_b128 v[6:9], v243 offset:8736
	v_lshl_add_u64 v[180:181], v[180:181], 0, s[100:101]
	v_lshl_add_u64 v[182:183], v[182:183], 0, s[100:101]
	s_waitcnt lgkmcnt(3)
	v_mfma_f32_32x32x16_bf16 v[96:111], v[10:13], v[120:123], v[96:111]
	ds_read_b128 v[10:13], v243 offset:8768
	v_lshl_add_u64 v[184:185], v[184:185], 0, s[100:101]
	v_lshl_add_u64 v[186:187], v[186:187], 0, s[24:25]
	s_waitcnt lgkmcnt(3)
	v_mfma_f32_32x32x16_bf16 v[96:111], v[252:255], v[124:127], v[96:111]
	ds_read_b128 v[252:255], v243 offset:8800
	v_lshl_add_u64 v[188:189], v[188:189], 0, s[24:25]
	v_lshl_add_u64 v[190:191], v[190:191], 0, s[24:25]
	s_waitcnt lgkmcnt(3)
	v_mfma_f32_32x32x16_bf16 v[80:95], v[2:5], v[112:115], v[80:95]
	ds_read_b64 v[2:3], v251
	ds_read_b64 v[4:5], v251 offset:16
	s_waitcnt lgkmcnt(4)
	v_mfma_f32_32x32x16_bf16 v[80:95], v[6:9], v[116:119], v[80:95]
	ds_read_b64 v[6:7], v251 offset:4352
	ds_read_b64 v[8:9], v251 offset:4368
	s_waitcnt lgkmcnt(5)
	v_mfma_f32_32x32x16_bf16 v[80:95], v[10:13], v[120:123], v[80:95]
	ds_read_b64 v[10:11], v251 offset:8704
	ds_read_b64 v[12:13], v251 offset:8720
	v_exp_f32_e32 v96, v96
	v_exp_f32_e32 v97, v97
	v_exp_f32_e32 v98, v98
	v_exp_f32_e32 v99, v99
	s_waitcnt lgkmcnt(6)
	v_mfma_f32_32x32x16_bf16 v[80:95], v[252:255], v[124:127], v[80:95]
	ds_read_b64 v[252:253], v251 offset:13056
	ds_read_b64 v[254:255], v251 offset:13072
	v_exp_f32_e32 v100, v100
	v_exp_f32_e32 v101, v101
	v_exp_f32_e32 v102, v102
	v_exp_f32_e32 v103, v103
	v_cvt_pk_bf16_f32 v242, v96, v97
	v_cvt_pk_bf16_f32 v243, v98, v99
	v_cvt_pk_bf16_f32 v244, v100, v101
	v_cvt_pk_bf16_f32 v245, v102, v103
	s_nop 0
	s_waitcnt lgkmcnt(6)
	v_mfma_f32_32x32x16_bf16 v[64:79], v[2:5], v[242:245], v[64:79]
	ds_read_b64 v[2:3], v251 offset:32
	ds_read_b64 v[4:5], v251 offset:48
	v_exp_f32_e32 v104, v104
	v_exp_f32_e32 v105, v105
	v_exp_f32_e32 v106, v106
	v_exp_f32_e32 v107, v107
	v_exp_f32_e32 v108, v108
	s_waitcnt lgkmcnt(6)
	v_mfma_f32_32x32x16_bf16 v[48:63], v[6:9], v[242:245], v[48:63]
	ds_read_b64 v[6:7], v251 offset:4384
	ds_read_b64 v[8:9], v251 offset:4400
	v_exp_f32_e32 v109, v109
	v_exp_f32_e32 v110, v110
	v_exp_f32_e32 v111, v111
	v_cvt_pk_bf16_f32 v246, v104, v105
	v_cvt_pk_bf16_f32 v247, v106, v107
	s_waitcnt lgkmcnt(6)
	v_mfma_f32_32x32x16_bf16 v[32:47], v[10:13], v[242:245], v[32:47]
	ds_read_b64 v[10:11], v251 offset:8736
	ds_read_b64 v[12:13], v251 offset:8752
	v_cvt_pk_bf16_f32 v248, v108, v109
	v_cvt_pk_bf16_f32 v249, v110, v111
	v_add_f32_e32 v96, v96, v97
	v_add_f32_e32 v98, v98, v99
	v_add_f32_e32 v100, v100, v101
	s_waitcnt lgkmcnt(6)
	v_mfma_f32_32x32x16_bf16 v[16:31], v[252:255], v[242:245], v[16:31]
	ds_read_b64 v[252:253], v251 offset:13088
	ds_read_b64 v[254:255], v251 offset:13104
	v_add_f32_e32 v102, v102, v103
	v_add_f32_e32 v96, v96, v98
	v_add_f32_e32 v100, v100, v102
	v_add_f32_e32 v96, v96, v100
	v_add_f32_e32 v239, v239, v96
	s_waitcnt lgkmcnt(6)
	v_mfma_f32_32x32x16_bf16 v[64:79], v[2:5], v[246:249], v[64:79]
	ds_read_b64 v[2:3], v251 offset:64
	ds_read_b64 v[4:5], v251 offset:80
	v_exp_f32_e32 v80, v80
	v_exp_f32_e32 v81, v81
	v_exp_f32_e32 v82, v82
	v_exp_f32_e32 v83, v83
	v_exp_f32_e32 v84, v84
	s_waitcnt lgkmcnt(6)
	v_mfma_f32_32x32x16_bf16 v[48:63], v[6:9], v[246:249], v[48:63]
	ds_read_b64 v[6:7], v251 offset:4416
	ds_read_b64 v[8:9], v251 offset:4432
	v_exp_f32_e32 v85, v85
	v_exp_f32_e32 v86, v86
	v_exp_f32_e32 v87, v87
	v_cvt_pk_bf16_f32 v242, v80, v81
	v_cvt_pk_bf16_f32 v243, v82, v83
	s_waitcnt lgkmcnt(6)
	v_mfma_f32_32x32x16_bf16 v[32:47], v[10:13], v[246:249], v[32:47]
	ds_read_b64 v[10:11], v251 offset:8768
	ds_read_b64 v[12:13], v251 offset:8784
	v_cvt_pk_bf16_f32 v244, v84, v85
	v_cvt_pk_bf16_f32 v245, v86, v87
	v_add_f32_e32 v104, v104, v105
	v_add_f32_e32 v106, v106, v107
	v_add_f32_e32 v108, v108, v109
	s_waitcnt lgkmcnt(6)
	v_mfma_f32_32x32x16_bf16 v[16:31], v[252:255], v[246:249], v[16:31]
	ds_read_b64 v[252:253], v251 offset:13120
	ds_read_b64 v[254:255], v251 offset:13136
	v_add_f32_e32 v110, v110, v111
	v_add_f32_e32 v104, v104, v106
	v_add_f32_e32 v108, v108, v110
	v_add_f32_e32 v104, v104, v108
	v_add_f32_e32 v239, v239, v104
	s_waitcnt lgkmcnt(6)
	v_mfma_f32_32x32x16_bf16 v[64:79], v[2:5], v[242:245], v[64:79]
	ds_read_b64 v[2:3], v251 offset:96
	ds_read_b64 v[4:5], v251 offset:112
	v_exp_f32_e32 v88, v88
	v_exp_f32_e32 v89, v89
	v_exp_f32_e32 v90, v90
	v_exp_f32_e32 v91, v91
	v_exp_f32_e32 v92, v92
	s_waitcnt lgkmcnt(6)
	v_mfma_f32_32x32x16_bf16 v[48:63], v[6:9], v[242:245], v[48:63]
	ds_read_b64 v[6:7], v251 offset:4448
	ds_read_b64 v[8:9], v251 offset:4464
	v_exp_f32_e32 v93, v93
	v_exp_f32_e32 v94, v94
	v_exp_f32_e32 v95, v95
	v_cvt_pk_bf16_f32 v246, v88, v89
	v_cvt_pk_bf16_f32 v247, v90, v91
	s_waitcnt lgkmcnt(6)
	v_mfma_f32_32x32x16_bf16 v[32:47], v[10:13], v[242:245], v[32:47]
	ds_read_b64 v[10:11], v251 offset:8800
	ds_read_b64 v[12:13], v251 offset:8816
	v_cvt_pk_bf16_f32 v248, v92, v93
	v_cvt_pk_bf16_f32 v249, v94, v95
	v_add_f32_e32 v80, v80, v81
	v_add_f32_e32 v82, v82, v83
	v_add_f32_e32 v84, v84, v85
	s_waitcnt lgkmcnt(6)
	v_mfma_f32_32x32x16_bf16 v[16:31], v[252:255], v[242:245], v[16:31]
	ds_read_b64 v[252:253], v251 offset:13152
	ds_read_b64 v[254:255], v251 offset:13168
	v_add_f32_e32 v86, v86, v87
	v_add_f32_e32 v80, v80, v82
	v_add_f32_e32 v84, v84, v86
	v_add_f32_e32 v80, v80, v84
	v_add_f32_e32 v239, v239, v80
	s_waitcnt lgkmcnt(6)
	v_mfma_f32_32x32x16_bf16 v[64:79], v[2:5], v[246:249], v[64:79]
	v_add_f32_e32 v88, v88, v89
	v_add_f32_e32 v90, v90, v91
	v_add_f32_e32 v92, v92, v93
	v_add_f32_e32 v94, v94, v95
	s_waitcnt lgkmcnt(4)
	v_mfma_f32_32x32x16_bf16 v[48:63], v[6:9], v[246:249], v[48:63]
	v_add_f32_e32 v88, v88, v90
	v_add_f32_e32 v92, v92, v94
	v_add_f32_e32 v88, v88, v92
	v_add_f32_e32 v239, v239, v88
	s_waitcnt lgkmcnt(2)
	v_mfma_f32_32x32x16_bf16 v[32:47], v[10:13], v[246:249], v[32:47]
	v_add_u32_e32 v232, -1, v232
	s_xor_b32 s42, s42, 1
	s_sub_i32 s6, s6, 64
	v_subrev_u32_e32 v238, 64, v238
	s_waitcnt lgkmcnt(0)
	v_mfma_f32_32x32x16_bf16 v[16:31], v[252:255], v[246:249], v[16:31]
	v_subrev_u32_e32 v241, 64, v241
	v_add_u32_e32 v240, 64, v240
	v_cmp_gt_u32_e64 s[4:5], 2, v232
	s_and_b64 vcc, exec, s[4:5]
	s_cbranch_vccz .LBB0_869
	s_branch .LBB0_879

.LBB0_877:
	v_add3_u32 v10, s43, v236, v234
	v_exp_f32_e32 v14, v97
	v_add_u32_e32 v97, 0x4000, v10
	ds_read2_b64 v[2:5], v97 offset0:128 offset1:130
	v_exp_f32_e32 v0, v96
	v_exp_f32_e32 v15, v98
	v_exp_f32_e32 v96, v99
	v_exp_f32_e32 v98, v100
	v_exp_f32_e32 v99, v101
	v_exp_f32_e32 v100, v102
	v_exp_f32_e32 v101, v103
	v_cvt_pk_bf16_f32 v6, v0, v14
	v_cvt_pk_bf16_f32 v7, v15, v96
	v_cvt_pk_bf16_f32 v8, v98, v99
	v_cvt_pk_bf16_f32 v9, v100, v101
	v_add_u32_e32 v102, 0x5000, v10
	v_add_u32_e32 v103, 0x6000, v10
	s_waitcnt lgkmcnt(0)
	v_mfma_f32_32x32x16_bf16 v[64:79], v[2:5], v[6:9], v[64:79]
	ds_read2_b64 v[2:5], v102 offset0:160 offset1:162
	v_add_u32_e32 v242, 0x7000, v10
	ds_read2_b64 v[10:13], v97 offset0:132 offset1:134
	v_exp_f32_e32 v104, v104
	v_exp_f32_e32 v105, v105
	v_exp_f32_e32 v106, v106
	v_exp_f32_e32 v107, v107
	s_waitcnt lgkmcnt(1)
	v_mfma_f32_32x32x16_bf16 v[48:63], v[2:5], v[6:9], v[48:63]
	ds_read2_b64 v[2:5], v103 offset0:192 offset1:194
	v_exp_f32_e32 v108, v108
	v_exp_f32_e32 v109, v109
	v_exp_f32_e32 v110, v110
	v_exp_f32_e32 v111, v111
	v_add_f32_e32 v0, 0, v0
	v_add_f32_e32 v0, v14, v0
	s_waitcnt lgkmcnt(0)
	v_mfma_f32_32x32x16_bf16 v[32:47], v[2:5], v[6:9], v[32:47]
	ds_read2_b64 v[2:5], v242 offset0:224 offset1:226
	v_add_f32_e32 v0, v15, v0
	v_add_f32_e32 v0, v96, v0
	v_add_f32_e32 v0, v98, v0
	v_exp_f32_e32 v14, v80
	v_exp_f32_e32 v15, v81
	v_exp_f32_e32 v80, v82
	s_waitcnt lgkmcnt(0)
	v_mfma_f32_32x32x16_bf16 v[16:31], v[2:5], v[6:9], v[16:31]
	ds_read2_b64 v[6:9], v102 offset0:164 offset1:166
	v_cvt_pk_bf16_f32 v2, v104, v105
	v_cvt_pk_bf16_f32 v3, v106, v107
	v_cvt_pk_bf16_f32 v4, v108, v109
	v_cvt_pk_bf16_f32 v5, v110, v111
	v_exp_f32_e32 v81, v83
	v_exp_f32_e32 v82, v84
	v_mfma_f32_32x32x16_bf16 v[64:79], v[10:13], v[2:5], v[64:79]
	ds_read2_b64 v[10:13], v103 offset0:196 offset1:198
	v_exp_f32_e32 v83, v85
	v_exp_f32_e32 v84, v86
	v_exp_f32_e32 v85, v87
	v_add_f32_e32 v0, v99, v0
	v_add_f32_e32 v0, v100, v0
	v_add_f32_e32 v0, v101, v0
	s_waitcnt lgkmcnt(1)
	v_mfma_f32_32x32x16_bf16 v[48:63], v[6:9], v[2:5], v[48:63]
	ds_read2_b64 v[6:9], v242 offset0:228 offset1:230
	v_add_f32_e32 v0, v104, v0
	v_add_f32_e32 v0, v105, v0
	v_add_f32_e32 v0, v106, v0
	v_add_f32_e32 v0, v107, v0
	v_add_f32_e32 v0, v108, v0
	v_add_f32_e32 v0, v109, v0
	s_waitcnt lgkmcnt(1)
	v_mfma_f32_32x32x16_bf16 v[32:47], v[10:13], v[2:5], v[32:47]
	ds_read2_b64 v[10:13], v97 offset0:136 offset1:138
	v_add_f32_e32 v0, v110, v0
	v_add_f32_e32 v0, v111, v0
	v_add_f32_e32 v0, v14, v0
	v_add_f32_e32 v0, v15, v0
	v_add_f32_e32 v0, v80, v0
	v_add_f32_e32 v0, v81, v0
	s_waitcnt lgkmcnt(1)
	v_mfma_f32_32x32x16_bf16 v[16:31], v[6:9], v[2:5], v[16:31]
	ds_read2_b64 v[6:9], v102 offset0:168 offset1:170
	v_cvt_pk_bf16_f32 v2, v14, v15
	v_cvt_pk_bf16_f32 v3, v80, v81
	v_cvt_pk_bf16_f32 v4, v82, v83
	v_cvt_pk_bf16_f32 v5, v84, v85
	v_add_f32_e32 v0, v82, v0
	v_add_f32_e32 v0, v83, v0
	s_waitcnt lgkmcnt(1)
	v_mfma_f32_32x32x16_bf16 v[64:79], v[10:13], v[2:5], v[64:79]
	ds_read2_b64 v[10:13], v103 offset0:200 offset1:202
	v_add_f32_e32 v0, v84, v0
	v_exp_f32_e32 v14, v88
	v_exp_f32_e32 v15, v89
	v_exp_f32_e32 v80, v90
	v_exp_f32_e32 v81, v91
	v_exp_f32_e32 v82, v92
	s_waitcnt lgkmcnt(1)
	v_mfma_f32_32x32x16_bf16 v[48:63], v[6:9], v[2:5], v[48:63]
	ds_read2_b64 v[6:9], v242 offset0:232 offset1:234
	v_exp_f32_e32 v83, v93
	v_exp_f32_e32 v84, v94
	v_exp_f32_e32 v86, v95
	v_add_f32_e32 v0, v85, v0
	v_add_f32_e32 v0, v14, v0
	v_add_f32_e32 v0, v15, v0
	s_waitcnt lgkmcnt(1)
	v_mfma_f32_32x32x16_bf16 v[32:47], v[10:13], v[2:5], v[32:47]
	ds_read2_b64 v[10:13], v97 offset0:140 offset1:142
	v_add_f32_e32 v0, v80, v0
	v_add_f32_e32 v0, v81, v0
	v_add_f32_e32 v0, v82, v0
	v_add_f32_e32 v0, v83, v0
	v_add_f32_e32 v0, v84, v0
	v_add_f32_e32 v0, v86, v0
	s_waitcnt lgkmcnt(1)
	v_mfma_f32_32x32x16_bf16 v[16:31], v[6:9], v[2:5], v[16:31]
	ds_read2_b64 v[6:9], v102 offset0:172 offset1:174
	v_cvt_pk_bf16_f32 v2, v14, v15
	v_cvt_pk_bf16_f32 v3, v80, v81
	v_cvt_pk_bf16_f32 v4, v82, v83
	v_cvt_pk_bf16_f32 v5, v84, v86
	v_add_u32_e32 v232, -1, v232
	v_add_f32_e32 v239, v239, v0
	s_waitcnt lgkmcnt(1)
	v_mfma_f32_32x32x16_bf16 v[64:79], v[10:13], v[2:5], v[64:79]
	ds_read2_b64 v[10:13], v103 offset0:204 offset1:206
	s_xor_b32 s42, s42, 1
	v_lshl_add_u64 v[176:177], v[176:177], 0, s[24:25]
	v_lshl_add_u64 v[178:179], v[178:179], 0, s[100:101]
	v_lshl_add_u64 v[180:181], v[180:181], 0, s[100:101]
	v_lshl_add_u64 v[182:183], v[182:183], 0, s[100:101]
	v_lshl_add_u64 v[184:185], v[184:185], 0, s[100:101]
	s_waitcnt lgkmcnt(1)
	v_mfma_f32_32x32x16_bf16 v[48:63], v[6:9], v[2:5], v[48:63]
	ds_read2_b64 v[6:9], v242 offset0:236 offset1:238
	v_lshl_add_u64 v[186:187], v[186:187], 0, s[24:25]
	v_lshl_add_u64 v[188:189], v[188:189], 0, s[24:25]
	v_lshl_add_u64 v[190:191], v[190:191], 0, s[24:25]
	s_sub_i32 s6, s6, 64
	v_subrev_u32_e32 v238, 64, v238
	v_subrev_u32_e32 v241, 64, v241
	s_waitcnt lgkmcnt(1)
	v_mfma_f32_32x32x16_bf16 v[32:47], v[10:13], v[2:5], v[32:47]
	v_add_u32_e32 v240, 64, v240
	v_cmp_gt_u32_e64 s[4:5], 2, v232
	s_waitcnt lgkmcnt(0)
	v_mfma_f32_32x32x16_bf16 v[16:31], v[6:9], v[2:5], v[16:31]
	s_and_b64 vcc, exec, s[4:5]
	s_cbranch_vccz .LBB0_869
	s_branch .LBB0_879
